# hgrn_pass_c epilogue output rows (full 128-byte lines) written through as well
# baseline (speedup 1.0000x reference)
.LBB0_1106:
	ds_read2st64_b32 v[28:29], v120 offset1:1
	v_and_b32_e32 v0, 64, v179
	v_add_u32_e32 v0, 64, v0
	v_xor_b32_e32 v26, 1, v179
	v_cmp_lt_i32_e32 vcc, v26, v0
	s_waitcnt lgkmcnt(0)
	v_pk_mul_f32 v[48:49], v[28:29], v[28:29]
	s_lshl_b32 s10, s4, 1
	v_cndmask_b32_e32 v26, v179, v26, vcc
	v_lshlrev_b32_e32 v47, 2, v26
	v_add_f32_e32 v48, v48, v49
	s_nop 1
	v_mov_b32_dpp v49, v48 quad_perm:[1,0,3,2] row_mask:0xf bank_mask:0xf
	v_xor_b32_e32 v26, 2, v179
	v_cmp_lt_i32_e32 vcc, v26, v0
	v_lshlrev_b64 v[42:43], 11, v[42:43]
	s_waitcnt lgkmcnt(0)
	v_add_f32_e32 v48, v48, v49
	v_cndmask_b32_e32 v26, v179, v26, vcc
	v_lshlrev_b32_e32 v46, 2, v26
	s_nop 1
	v_mov_b32_dpp v49, v48 quad_perm:[2,3,0,1] row_mask:0xf bank_mask:0xf
	v_xor_b32_e32 v26, 4, v179
	v_cmp_lt_i32_e32 vcc, v26, v0
	s_waitcnt lgkmcnt(0)
	v_add_f32_e32 v48, v48, v49
	v_cndmask_b32_e32 v26, v179, v26, vcc
	v_lshlrev_b32_e32 v45, 2, v26
	s_nop 1
	v_mov_b32_dpp v49, v48 row_shl:4 row_mask:0xf bank_mask:0x5
	s_nop 1
	v_mov_b32_dpp v49, v48 row_shr:4 row_mask:0xf bank_mask:0xa
	v_xor_b32_e32 v26, 8, v179
	v_cmp_lt_i32_e32 vcc, v26, v0
	s_waitcnt lgkmcnt(0)
	v_add_f32_e32 v48, v48, v49
	v_cndmask_b32_e32 v26, v179, v26, vcc
	v_lshlrev_b32_e32 v44, 2, v26
	s_nop 1
	v_mov_b32_dpp v49, v48 row_shl:8 row_mask:0xf bank_mask:0x3
	s_nop 1
	v_mov_b32_dpp v49, v48 row_shr:8 row_mask:0xf bank_mask:0xc
	v_xor_b32_e32 v26, 16, v179
	v_cmp_lt_i32_e32 vcc, v26, v0
	s_waitcnt lgkmcnt(0)
	v_add_f32_e32 v48, v48, v49
	v_cndmask_b32_e32 v26, v179, v26, vcc
	v_lshlrev_b32_e32 v41, 2, v26
	v_mov_b32_e32 v49, v48
	s_nop 1
	v_permlane16_swap_b32 v49, v48
	v_xor_b32_e32 v26, 32, v179
	v_cmp_lt_i32_e32 vcc, v26, v0
	s_waitcnt lgkmcnt(0)
	v_add_f32_e32 v48, v48, v49
	v_cndmask_b32_e32 v0, v179, v26, vcc
	v_lshlrev_b32_e32 v0, 2, v0
	v_mov_b32_e32 v49, v48
	s_nop 1
	v_permlane32_swap_b32 v49, v48
	v_lshl_add_u64 v[26:27], v[36:37], 0, s[10:11]
	v_lshl_add_u64 v[42:43], v[26:27], 0, v[42:43]
	s_waitcnt lgkmcnt(0)
	v_add_f32_e32 v48, v48, v49
	v_fmamk_f32 v48, v48, 0x3c000000, v184
	v_cmp_gt_f32_e32 vcc, s29, v48
	v_mul_f32_e32 v49, 0x4b800000, v48
	s_nop 0
	v_cndmask_b32_e32 v48, v48, v49, vcc
	v_rsq_f32_e32 v48, v48
	s_nop 0
	v_mul_f32_e32 v49, 0x45800000, v48
	v_cndmask_b32_e32 v48, v48, v49, vcc
	s_waitcnt vmcnt(15)
	v_lshlrev_b32_e32 v49, 16, v150
	v_mul_f32_e32 v50, 0xbfb8aa3b, v49
	v_exp_f32_e32 v50, v50
	v_mul_f32_e32 v28, v28, v48
	v_mul_f32_e32 v28, v137, v28
	v_add_f32_e32 v50, 1.0, v50
	v_rcp_f32_e32 v50, v50
	s_nop 0
	v_mul_f32_e32 v49, v50, v49
	v_mul_f32_e32 v28, v49, v28
	v_cvt_pk_bf16_f32 v28, v28, v28
	global_store_short v[42:43], v28, off sc1
	v_mul_f32_e32 v28, v29, v48
	s_waitcnt vmcnt(15)
	v_lshlrev_b32_e32 v29, 16, v151
	v_mul_f32_e32 v48, 0xbfb8aa3b, v29
	v_exp_f32_e32 v48, v48
	v_mul_f32_e32 v28, v159, v28
	v_add_f32_e32 v48, 1.0, v48
	v_rcp_f32_e32 v48, v48
	s_nop 0
	v_mul_f32_e32 v29, v48, v29
	v_mul_f32_e32 v28, v29, v28
	v_cvt_pk_bf16_f32 v28, v28, v28
	global_store_short v[42:43], v28, off offset:128 sc1
	ds_read2st64_b32 v[42:43], v122 offset1:1
	v_add_u32_e32 v28, s93, v121
	s_waitcnt lgkmcnt(0)
	v_pk_mul_f32 v[48:49], v[42:43], v[42:43]
	v_add_f32_e32 v29, v48, v49
	s_nop 1
	v_mov_b32_dpp v48, v29 quad_perm:[1,0,3,2] row_mask:0xf bank_mask:0xf
	s_waitcnt lgkmcnt(0)
	v_add_f32_e32 v29, v29, v48
	s_nop 1
	v_mov_b32_dpp v48, v29 quad_perm:[2,3,0,1] row_mask:0xf bank_mask:0xf
	s_waitcnt lgkmcnt(0)
	v_add_f32_e32 v29, v29, v48
	s_nop 1
	v_mov_b32_dpp v48, v29 row_shl:4 row_mask:0xf bank_mask:0x5
	s_nop 1
	v_mov_b32_dpp v48, v29 row_shr:4 row_mask:0xf bank_mask:0xa
	s_waitcnt lgkmcnt(0)
	v_add_f32_e32 v29, v29, v48
	s_nop 1
	v_mov_b32_dpp v48, v29 row_shl:8 row_mask:0xf bank_mask:0x3
	s_nop 1
	v_mov_b32_dpp v48, v29 row_shr:8 row_mask:0xf bank_mask:0xc
	s_waitcnt lgkmcnt(0)
	v_add_f32_e32 v29, v29, v48
	v_mov_b32_e32 v48, v29
	s_nop 1
	v_permlane16_swap_b32 v48, v29
	s_waitcnt lgkmcnt(0)
	v_add_f32_e32 v29, v29, v48
	v_mov_b32_e32 v48, v29
	s_nop 1
	v_permlane32_swap_b32 v48, v29
	s_waitcnt lgkmcnt(0)
	v_add_f32_e32 v29, v29, v48
	v_fmamk_f32 v29, v29, 0x3c000000, v184
	v_cmp_gt_f32_e32 vcc, s29, v29
	v_mul_f32_e32 v48, 0x4b800000, v29
	s_nop 0
	v_cndmask_b32_e32 v29, v29, v48, vcc
	v_rsq_f32_e32 v29, v29
	s_nop 0
	v_mul_f32_e32 v48, 0x45800000, v29
	v_cndmask_b32_e32 v48, v29, v48, vcc
	v_mul_f32_e32 v29, v42, v48
	s_waitcnt vmcnt(15)
	v_lshlrev_b32_e32 v42, 16, v152
	v_mul_f32_e32 v49, 0xbfb8aa3b, v42
	v_exp_f32_e32 v49, v49
	v_mul_f32_e32 v29, v137, v29
	v_add_f32_e32 v49, 1.0, v49
	v_rcp_f32_e32 v49, v49
	s_nop 0
	v_mul_f32_e32 v42, v49, v42
	v_mul_f32_e32 v29, v42, v29
	v_cvt_pk_bf16_f32 v42, v29, v29
	v_ashrrev_i32_e32 v29, 31, v28
	v_lshlrev_b64 v[28:29], 11, v[28:29]
	v_lshl_add_u64 v[28:29], v[26:27], 0, v[28:29]
	global_store_short v[28:29], v42, off sc1
	v_mul_f32_e32 v42, v43, v48
	s_waitcnt vmcnt(15)
	v_lshlrev_b32_e32 v43, 16, v153
	v_mul_f32_e32 v48, 0xbfb8aa3b, v43
	v_exp_f32_e32 v48, v48
	v_mul_f32_e32 v42, v159, v42
	v_add_f32_e32 v48, 1.0, v48
	v_rcp_f32_e32 v48, v48
	s_nop 0
	v_mul_f32_e32 v43, v48, v43
	v_mul_f32_e32 v42, v43, v42
	v_cvt_pk_bf16_f32 v42, v42, v42
	global_store_short v[28:29], v42, off offset:128 sc1
	ds_read2st64_b32 v[42:43], v126 offset1:1
	v_add_u32_e32 v28, s93, v123
	s_waitcnt lgkmcnt(0)
	v_pk_mul_f32 v[48:49], v[42:43], v[42:43]
	v_add_f32_e32 v29, v48, v49
	s_nop 1
	v_mov_b32_dpp v48, v29 quad_perm:[1,0,3,2] row_mask:0xf bank_mask:0xf
	s_waitcnt lgkmcnt(0)
	v_add_f32_e32 v29, v29, v48
	s_nop 1
	v_mov_b32_dpp v48, v29 quad_perm:[2,3,0,1] row_mask:0xf bank_mask:0xf
	s_waitcnt lgkmcnt(0)
	v_add_f32_e32 v29, v29, v48
	s_nop 1
	v_mov_b32_dpp v48, v29 row_shl:4 row_mask:0xf bank_mask:0x5
	s_nop 1
	v_mov_b32_dpp v48, v29 row_shr:4 row_mask:0xf bank_mask:0xa
	s_waitcnt lgkmcnt(0)
	v_add_f32_e32 v29, v29, v48
	s_nop 1
	v_mov_b32_dpp v48, v29 row_shl:8 row_mask:0xf bank_mask:0x3
	s_nop 1
	v_mov_b32_dpp v48, v29 row_shr:8 row_mask:0xf bank_mask:0xc
	s_waitcnt lgkmcnt(0)
	v_add_f32_e32 v29, v29, v48
	v_mov_b32_e32 v48, v29
	s_nop 1
	v_permlane16_swap_b32 v48, v29
	s_waitcnt lgkmcnt(0)
	v_add_f32_e32 v29, v29, v48
	v_mov_b32_e32 v48, v29
	s_nop 1
	v_permlane32_swap_b32 v48, v29
	s_waitcnt lgkmcnt(0)
	v_add_f32_e32 v29, v29, v48
	v_fmamk_f32 v29, v29, 0x3c000000, v184
	v_cmp_gt_f32_e32 vcc, s29, v29
	v_mul_f32_e32 v48, 0x4b800000, v29
	s_nop 0
	v_cndmask_b32_e32 v29, v29, v48, vcc
	v_rsq_f32_e32 v29, v29
	s_nop 0
	v_mul_f32_e32 v48, 0x45800000, v29
	v_cndmask_b32_e32 v48, v29, v48, vcc
	v_mul_f32_e32 v29, v42, v48
	s_waitcnt vmcnt(15)
	v_lshlrev_b32_e32 v42, 16, v154
	v_mul_f32_e32 v49, 0xbfb8aa3b, v42
	v_exp_f32_e32 v49, v49
	v_mul_f32_e32 v29, v137, v29
	v_add_f32_e32 v49, 1.0, v49
	v_rcp_f32_e32 v49, v49
	s_nop 0
	v_mul_f32_e32 v42, v49, v42
	v_mul_f32_e32 v29, v42, v29
	v_cvt_pk_bf16_f32 v42, v29, v29
	v_ashrrev_i32_e32 v29, 31, v28
	v_lshlrev_b64 v[28:29], 11, v[28:29]
	v_lshl_add_u64 v[28:29], v[26:27], 0, v[28:29]
	global_store_short v[28:29], v42, off sc1
	v_mul_f32_e32 v42, v43, v48
	s_waitcnt vmcnt(15)
	v_lshlrev_b32_e32 v43, 16, v155
	v_mul_f32_e32 v48, 0xbfb8aa3b, v43
	v_exp_f32_e32 v48, v48
	v_mul_f32_e32 v42, v159, v42
	v_add_f32_e32 v48, 1.0, v48
	v_rcp_f32_e32 v48, v48
	s_nop 0
	v_mul_f32_e32 v43, v48, v43
	v_mul_f32_e32 v42, v43, v42
	v_cvt_pk_bf16_f32 v42, v42, v42
	global_store_short v[28:29], v42, off offset:128 sc1
	ds_read2st64_b32 v[42:43], v128 offset1:1
	v_add_u32_e32 v28, s93, v127
	s_waitcnt lgkmcnt(0)
	v_pk_mul_f32 v[48:49], v[42:43], v[42:43]
	v_add_f32_e32 v29, v48, v49
	s_nop 1
	v_mov_b32_dpp v48, v29 quad_perm:[1,0,3,2] row_mask:0xf bank_mask:0xf
	s_waitcnt lgkmcnt(0)
	v_add_f32_e32 v29, v29, v48
	s_nop 1
	v_mov_b32_dpp v48, v29 quad_perm:[2,3,0,1] row_mask:0xf bank_mask:0xf
	s_waitcnt lgkmcnt(0)
	v_add_f32_e32 v29, v29, v48
	s_nop 1
	v_mov_b32_dpp v48, v29 row_shl:4 row_mask:0xf bank_mask:0x5
	s_nop 1
	v_mov_b32_dpp v48, v29 row_shr:4 row_mask:0xf bank_mask:0xa
	s_waitcnt lgkmcnt(0)
	v_add_f32_e32 v29, v29, v48
	s_nop 1
	v_mov_b32_dpp v48, v29 row_shl:8 row_mask:0xf bank_mask:0x3
	s_nop 1
	v_mov_b32_dpp v48, v29 row_shr:8 row_mask:0xf bank_mask:0xc
	s_waitcnt lgkmcnt(0)
	v_add_f32_e32 v29, v29, v48
	v_mov_b32_e32 v48, v29
	s_nop 1
	v_permlane16_swap_b32 v48, v29
	s_waitcnt lgkmcnt(0)
	v_add_f32_e32 v29, v29, v48
	v_mov_b32_e32 v48, v29
	s_nop 1
	v_permlane32_swap_b32 v48, v29
	s_waitcnt lgkmcnt(0)
	v_add_f32_e32 v29, v29, v48
	v_fmamk_f32 v29, v29, 0x3c000000, v184
	v_cmp_gt_f32_e32 vcc, s29, v29
	v_mul_f32_e32 v48, 0x4b800000, v29
	s_nop 0
	v_cndmask_b32_e32 v29, v29, v48, vcc
	v_rsq_f32_e32 v29, v29
	s_nop 0
	v_mul_f32_e32 v48, 0x45800000, v29
	v_cndmask_b32_e32 v48, v29, v48, vcc
	v_mul_f32_e32 v29, v42, v48
	s_waitcnt vmcnt(15)
	v_lshlrev_b32_e32 v42, 16, v156
	v_mul_f32_e32 v49, 0xbfb8aa3b, v42
	v_exp_f32_e32 v49, v49
	v_mul_f32_e32 v29, v137, v29
	v_add_f32_e32 v49, 1.0, v49
	v_rcp_f32_e32 v49, v49
	s_nop 0
	v_mul_f32_e32 v42, v49, v42
	v_mul_f32_e32 v29, v42, v29
	v_cvt_pk_bf16_f32 v42, v29, v29
	v_ashrrev_i32_e32 v29, 31, v28
	v_lshlrev_b64 v[28:29], 11, v[28:29]
	v_lshl_add_u64 v[28:29], v[26:27], 0, v[28:29]
	global_store_short v[28:29], v42, off sc1
	v_mul_f32_e32 v42, v43, v48
	s_waitcnt vmcnt(15)
	v_lshlrev_b32_e32 v43, 16, v157
	v_mul_f32_e32 v48, 0xbfb8aa3b, v43
	v_exp_f32_e32 v48, v48
	v_mul_f32_e32 v42, v159, v42
	v_add_f32_e32 v48, 1.0, v48
	v_rcp_f32_e32 v48, v48
	s_nop 0
	v_mul_f32_e32 v43, v48, v43
	v_mul_f32_e32 v42, v43, v42
	v_cvt_pk_bf16_f32 v42, v42, v42
	global_store_short v[28:29], v42, off offset:128 sc1
	ds_read2st64_b32 v[42:43], v130 offset1:1
	v_add_u32_e32 v28, s93, v129
	s_waitcnt lgkmcnt(0)
	v_pk_mul_f32 v[48:49], v[42:43], v[42:43]
	v_add_f32_e32 v29, v48, v49
	s_nop 1
	v_mov_b32_dpp v48, v29 quad_perm:[1,0,3,2] row_mask:0xf bank_mask:0xf
	s_waitcnt lgkmcnt(0)
	v_add_f32_e32 v29, v29, v48
	s_nop 1
	v_mov_b32_dpp v48, v29 quad_perm:[2,3,0,1] row_mask:0xf bank_mask:0xf
	s_waitcnt lgkmcnt(0)
	v_add_f32_e32 v29, v29, v48
	s_nop 1
	v_mov_b32_dpp v48, v29 row_shl:4 row_mask:0xf bank_mask:0x5
	s_nop 1
	v_mov_b32_dpp v48, v29 row_shr:4 row_mask:0xf bank_mask:0xa
	s_waitcnt lgkmcnt(0)
	v_add_f32_e32 v29, v29, v48
	s_nop 1
	v_mov_b32_dpp v48, v29 row_shl:8 row_mask:0xf bank_mask:0x3
	s_nop 1
	v_mov_b32_dpp v48, v29 row_shr:8 row_mask:0xf bank_mask:0xc
	s_waitcnt lgkmcnt(0)
	v_add_f32_e32 v29, v29, v48
	v_mov_b32_e32 v48, v29
	s_nop 1
	v_permlane16_swap_b32 v48, v29
	s_waitcnt lgkmcnt(0)
	v_add_f32_e32 v29, v29, v48
	v_mov_b32_e32 v48, v29
	s_nop 1
	v_permlane32_swap_b32 v48, v29
	s_waitcnt lgkmcnt(0)
	v_add_f32_e32 v29, v29, v48
	v_fmamk_f32 v29, v29, 0x3c000000, v184
	v_cmp_gt_f32_e32 vcc, s29, v29
	v_mul_f32_e32 v48, 0x4b800000, v29
	s_nop 0
	v_cndmask_b32_e32 v29, v29, v48, vcc
	v_rsq_f32_e32 v29, v29
	s_nop 0
	v_mul_f32_e32 v48, 0x45800000, v29
	v_cndmask_b32_e32 v48, v29, v48, vcc
	v_mul_f32_e32 v29, v42, v48
	s_waitcnt vmcnt(15)
	v_lshlrev_b32_e32 v42, 16, v158
	v_mul_f32_e32 v49, 0xbfb8aa3b, v42
	v_exp_f32_e32 v49, v49
	v_mul_f32_e32 v29, v137, v29
	v_add_f32_e32 v49, 1.0, v49
	v_rcp_f32_e32 v49, v49
	s_nop 0
	v_mul_f32_e32 v42, v49, v42
	v_mul_f32_e32 v29, v42, v29
	v_cvt_pk_bf16_f32 v42, v29, v29
	v_ashrrev_i32_e32 v29, 31, v28
	v_lshlrev_b64 v[28:29], 11, v[28:29]
	v_lshl_add_u64 v[28:29], v[26:27], 0, v[28:29]
	global_store_short v[28:29], v42, off sc1
	v_mul_f32_e32 v42, v43, v48
	s_waitcnt vmcnt(15)
	v_lshlrev_b32_e32 v43, 16, v164
	v_mul_f32_e32 v48, 0xbfb8aa3b, v43
	v_exp_f32_e32 v48, v48
	v_mul_f32_e32 v42, v159, v42
	v_add_f32_e32 v48, 1.0, v48
	v_rcp_f32_e32 v48, v48
	s_nop 0
	v_mul_f32_e32 v43, v48, v43
	v_mul_f32_e32 v42, v43, v42
	v_cvt_pk_bf16_f32 v42, v42, v42
	global_store_short v[28:29], v42, off offset:128 sc1
	ds_read2st64_b32 v[42:43], v132 offset1:1
	v_add_u32_e32 v28, s93, v131
	s_waitcnt lgkmcnt(0)
	v_pk_mul_f32 v[48:49], v[42:43], v[42:43]
	v_add_f32_e32 v29, v48, v49
	s_nop 1
	v_mov_b32_dpp v48, v29 quad_perm:[1,0,3,2] row_mask:0xf bank_mask:0xf
	s_waitcnt lgkmcnt(0)
	v_add_f32_e32 v29, v29, v48
	s_nop 1
	v_mov_b32_dpp v48, v29 quad_perm:[2,3,0,1] row_mask:0xf bank_mask:0xf
	s_waitcnt lgkmcnt(0)
	v_add_f32_e32 v29, v29, v48
	s_nop 1
	v_mov_b32_dpp v48, v29 row_shl:4 row_mask:0xf bank_mask:0x5
	s_nop 1
	v_mov_b32_dpp v48, v29 row_shr:4 row_mask:0xf bank_mask:0xa
	s_waitcnt lgkmcnt(0)
	v_add_f32_e32 v29, v29, v48
	s_nop 1
	v_mov_b32_dpp v48, v29 row_shl:8 row_mask:0xf bank_mask:0x3
	s_nop 1
	v_mov_b32_dpp v48, v29 row_shr:8 row_mask:0xf bank_mask:0xc
	s_waitcnt lgkmcnt(0)
	v_add_f32_e32 v29, v29, v48
	v_mov_b32_e32 v48, v29
	s_nop 1
	v_permlane16_swap_b32 v48, v29
	s_waitcnt lgkmcnt(0)
	v_add_f32_e32 v29, v29, v48
	v_mov_b32_e32 v48, v29
	s_nop 1
	v_permlane32_swap_b32 v48, v29
	s_waitcnt lgkmcnt(0)
	v_add_f32_e32 v29, v29, v48
	v_fmamk_f32 v29, v29, 0x3c000000, v184
	v_cmp_gt_f32_e32 vcc, s29, v29
	v_mul_f32_e32 v48, 0x4b800000, v29
	s_nop 0
	v_cndmask_b32_e32 v29, v29, v48, vcc
	v_rsq_f32_e32 v29, v29
	s_nop 0
	v_mul_f32_e32 v48, 0x45800000, v29
	v_cndmask_b32_e32 v48, v29, v48, vcc
	v_mul_f32_e32 v29, v42, v48
	s_waitcnt vmcnt(15)
	v_lshlrev_b32_e32 v42, 16, v165
	v_mul_f32_e32 v49, 0xbfb8aa3b, v42
	v_exp_f32_e32 v49, v49
	v_mul_f32_e32 v29, v137, v29
	v_add_f32_e32 v49, 1.0, v49
	v_rcp_f32_e32 v49, v49
	s_nop 0
	v_mul_f32_e32 v42, v49, v42
	v_mul_f32_e32 v29, v42, v29
	v_cvt_pk_bf16_f32 v42, v29, v29
	v_ashrrev_i32_e32 v29, 31, v28
	v_lshlrev_b64 v[28:29], 11, v[28:29]
	v_lshl_add_u64 v[28:29], v[26:27], 0, v[28:29]
	global_store_short v[28:29], v42, off sc1
	v_mul_f32_e32 v42, v43, v48
	s_waitcnt vmcnt(15)
	v_lshlrev_b32_e32 v43, 16, v166
	v_mul_f32_e32 v48, 0xbfb8aa3b, v43
	v_exp_f32_e32 v48, v48
	v_mul_f32_e32 v42, v159, v42
	v_add_f32_e32 v48, 1.0, v48
	v_rcp_f32_e32 v48, v48
	s_nop 0
	v_mul_f32_e32 v43, v48, v43
	v_mul_f32_e32 v42, v43, v42
	v_cvt_pk_bf16_f32 v42, v42, v42
	global_store_short v[28:29], v42, off offset:128 sc1
	ds_read2st64_b32 v[42:43], v134 offset1:1
	v_add_u32_e32 v28, s93, v133
	s_waitcnt lgkmcnt(0)
	v_pk_mul_f32 v[48:49], v[42:43], v[42:43]
	v_add_f32_e32 v29, v48, v49
	s_nop 1
	v_mov_b32_dpp v48, v29 quad_perm:[1,0,3,2] row_mask:0xf bank_mask:0xf
	s_waitcnt lgkmcnt(0)
	v_add_f32_e32 v29, v29, v48
	s_nop 1
	v_mov_b32_dpp v48, v29 quad_perm:[2,3,0,1] row_mask:0xf bank_mask:0xf
	s_waitcnt lgkmcnt(0)
	v_add_f32_e32 v29, v29, v48
	s_nop 1
	v_mov_b32_dpp v48, v29 row_shl:4 row_mask:0xf bank_mask:0x5
	s_nop 1
	v_mov_b32_dpp v48, v29 row_shr:4 row_mask:0xf bank_mask:0xa
	s_waitcnt lgkmcnt(0)
	v_add_f32_e32 v29, v29, v48
	s_nop 1
	v_mov_b32_dpp v48, v29 row_shl:8 row_mask:0xf bank_mask:0x3
	s_nop 1
	v_mov_b32_dpp v48, v29 row_shr:8 row_mask:0xf bank_mask:0xc
	s_waitcnt lgkmcnt(0)
	v_add_f32_e32 v29, v29, v48
	v_mov_b32_e32 v48, v29
	s_nop 1
	v_permlane16_swap_b32 v48, v29
	s_waitcnt lgkmcnt(0)
	v_add_f32_e32 v29, v29, v48
	v_mov_b32_e32 v48, v29
	s_nop 1
	v_permlane32_swap_b32 v48, v29
	s_waitcnt lgkmcnt(0)
	v_add_f32_e32 v29, v29, v48
	v_fmamk_f32 v29, v29, 0x3c000000, v184
	v_cmp_gt_f32_e32 vcc, s29, v29
	v_mul_f32_e32 v48, 0x4b800000, v29
	s_nop 0
	v_cndmask_b32_e32 v29, v29, v48, vcc
	v_rsq_f32_e32 v29, v29
	s_nop 0
	v_mul_f32_e32 v48, 0x45800000, v29
	v_cndmask_b32_e32 v48, v29, v48, vcc
	v_mul_f32_e32 v29, v42, v48
	s_waitcnt vmcnt(15)
	v_lshlrev_b32_e32 v42, 16, v167
	v_mul_f32_e32 v49, 0xbfb8aa3b, v42
	v_exp_f32_e32 v49, v49
	v_mul_f32_e32 v29, v137, v29
	v_add_f32_e32 v49, 1.0, v49
	v_rcp_f32_e32 v49, v49
	s_nop 0
	v_mul_f32_e32 v42, v49, v42
	v_mul_f32_e32 v29, v42, v29
	v_cvt_pk_bf16_f32 v42, v29, v29
	v_ashrrev_i32_e32 v29, 31, v28
	v_lshlrev_b64 v[28:29], 11, v[28:29]
	v_lshl_add_u64 v[28:29], v[26:27], 0, v[28:29]
	global_store_short v[28:29], v42, off sc1
	v_mul_f32_e32 v42, v43, v48
	s_waitcnt vmcnt(15)
	v_lshlrev_b32_e32 v43, 16, v168
	v_mul_f32_e32 v48, 0xbfb8aa3b, v43
	v_exp_f32_e32 v48, v48
	v_mul_f32_e32 v42, v159, v42
	v_add_f32_e32 v48, 1.0, v48
	v_rcp_f32_e32 v48, v48
	s_nop 0
	v_mul_f32_e32 v43, v48, v43
	v_mul_f32_e32 v42, v43, v42
	v_cvt_pk_bf16_f32 v42, v42, v42
	global_store_short v[28:29], v42, off offset:128 sc1
	ds_read2st64_b32 v[42:43], v136 offset1:1
	v_add_u32_e32 v28, s93, v135
	s_waitcnt lgkmcnt(0)
	v_pk_mul_f32 v[48:49], v[42:43], v[42:43]
	v_add_f32_e32 v29, v48, v49
	s_nop 1
	v_mov_b32_dpp v47, v29 quad_perm:[1,0,3,2] row_mask:0xf bank_mask:0xf
	s_waitcnt lgkmcnt(0)
	v_add_f32_e32 v29, v29, v47
	s_nop 1
	v_mov_b32_dpp v46, v29 quad_perm:[2,3,0,1] row_mask:0xf bank_mask:0xf
	s_waitcnt lgkmcnt(0)
	v_add_f32_e32 v29, v29, v46
	s_nop 1
	v_mov_b32_dpp v45, v29 row_shl:4 row_mask:0xf bank_mask:0x5
	s_nop 1
	v_mov_b32_dpp v45, v29 row_shr:4 row_mask:0xf bank_mask:0xa
	s_waitcnt lgkmcnt(0)
	v_add_f32_e32 v29, v29, v45
	s_nop 1
	v_mov_b32_dpp v44, v29 row_shl:8 row_mask:0xf bank_mask:0x3
	s_nop 1
	v_mov_b32_dpp v44, v29 row_shr:8 row_mask:0xf bank_mask:0xc
	s_waitcnt lgkmcnt(0)
	v_add_f32_e32 v29, v29, v44
	v_mov_b32_e32 v41, v29
	s_nop 1
	v_permlane16_swap_b32 v41, v29
	s_waitcnt lgkmcnt(0)
	v_add_f32_e32 v29, v29, v41
	v_mov_b32_e32 v0, v29
	s_nop 1
	v_permlane32_swap_b32 v0, v29
	s_waitcnt vmcnt(15)
	v_lshlrev_b32_e32 v41, 16, v169
	s_waitcnt lgkmcnt(0)
	v_add_f32_e32 v0, v29, v0
	v_fmamk_f32 v0, v0, 0x3c000000, v184
	v_cmp_gt_f32_e32 vcc, s29, v0
	v_mul_f32_e32 v29, 0x4b800000, v0
	s_nop 0
	v_cndmask_b32_e32 v0, v0, v29, vcc
	v_rsq_f32_e32 v0, v0
	s_nop 0
	v_mul_f32_e32 v29, 0x45800000, v0
	v_cndmask_b32_e32 v0, v0, v29, vcc
	v_mul_f32_e32 v29, v42, v0
	v_mul_f32_e32 v42, 0xbfb8aa3b, v41
	v_exp_f32_e32 v42, v42
	v_mul_f32_e32 v29, v137, v29
	v_mul_f32_e32 v0, v43, v0
	v_mul_f32_e32 v0, v159, v0
	v_add_f32_e32 v42, 1.0, v42
	v_rcp_f32_e32 v42, v42
	s_nop 0
	v_mul_f32_e32 v41, v42, v41
	v_mul_f32_e32 v29, v41, v29
	v_cvt_pk_bf16_f32 v41, v29, v29
	v_ashrrev_i32_e32 v29, 31, v28
	v_lshlrev_b64 v[28:29], 11, v[28:29]
	v_lshl_add_u64 v[26:27], v[26:27], 0, v[28:29]
	s_waitcnt vmcnt(14)
	v_lshlrev_b32_e32 v28, 16, v170
	v_mul_f32_e32 v29, 0xbfb8aa3b, v28
	v_exp_f32_e32 v29, v29
	global_store_short v[26:27], v41, off sc1
	v_add_f32_e32 v29, 1.0, v29
	v_readlane_b32 s0, v252, 0
	v_readlane_b32 s1, v252, 1
	v_rcp_f32_e32 v29, v29
	s_nop 0
	v_mul_f32_e32 v28, v29, v28
	v_mul_f32_e32 v0, v28, v0
	v_cvt_pk_bf16_f32 v0, v0, v0
	global_store_short v[26:27], v0, off offset:128 sc1
	s_waitcnt lgkmcnt(0)
	s_barrier
	s_load_dword s0, s[0:1], 0x10
	s_waitcnt lgkmcnt(0)
	s_lshr_b32 s0, s0, 16
	s_cmp_lg_u32 s0, 0
	s_cselect_b64 s[0:1], -1, 0
	s_cmp_lg_u64 s[0:1], 0
	s_addc_u32 s94, s92, 0
	s_cmpk_gt_i32 s94, 0x1ff
	s_cbranch_scc1 .LBB0_1190
